# NA attention tasks: the two compiler-inserted s_waitcnt vmcnt(0) before the first QK MFMA (they drained the whole 7-row LDS-DMA prefetch ring) relaxed to lgkmcnt(0); the q fragments are already retire
# speedup vs baseline: 1.0171x; 1.0022x over previous
.LBB0_866:
	s_or_b64 exec, exec, s[38:39]
	s_max_i32 s39, s49, 4
	s_add_i32 s39, s39, -4
	s_min_u32 s60, s39, s59
	s_max_i32 s39, s49, 3
	s_add_i32 s39, s39, -3
	s_min_u32 s61, s39, s59
	s_add_i32 s38, s58, s52
	s_sub_i32 s77, s61, s60
	s_and_b64 s[58:59], s[8:9], exec
	s_cselect_b32 s58, s60, s61
	s_ashr_i32 s39, s38, 31
	s_lshl_b64 s[38:39], s[38:39], 6
	v_mov_b32_e32 v17, s39
	v_or_b32_e32 v16, s38, v82
	v_mad_i64_i32 v[0:1], s[38:39], s48, v133, v[16:17]
	s_mul_i32 s38, s48, 0x6000
	s_add_i32 s39, s48, 16
	s_add_i32 s59, s38, 0x60000
	s_lshl_b32 s64, s60, 6
	s_add_u32 s64, s2, s64
	s_addc_u32 s65, s3, 0
	s_mul_hi_i32 s39, s39, 0x6000
	s_add_u32 s2, s64, s59
	s_addc_u32 s3, s65, s39
	s_lshl_b64 s[2:3], s[2:3], 8
	v_readlane_b32 s36, v253, 18
	v_readlane_b32 s37, v253, 19
	s_add_u32 s75, s36, s2
	s_addc_u32 s76, s37, s3
	s_add_i32 s2, s48, 32
	s_add_i32 s38, s38, 0xc0000
	s_mul_hi_i32 s3, s2, 0x6000
	s_add_u32 s2, s64, s38
	s_addc_u32 s3, s65, s3
	s_lshl_b64 s[2:3], s[2:3], 8
	s_add_u32 s72, s36, s2
	s_addc_u32 s73, s37, s3
	s_add_i32 s2, s49, s52
	s_sub_i32 s2, s58, s2
	s_mulk_i32 s2, 0x7c
	s_add_i32 s74, s2, 0
	s_lshl_b32 s38, s48, 7
	s_add_i32 s74, s74, 0x20400
	s_ashr_i32 s39, s38, 31
	s_cmp_eq_u32 s61, s60
	s_cselect_b64 s[2:3], -1, 0
	s_add_i32 s77, s77, 7
	s_min_i32 s48, s77, 0
	s_ashr_i32 s49, s48, 31
	s_or_b64 s[2:3], s[8:9], s[2:3]
	s_lshl_b64 s[90:91], s[48:49], 14
	s_add_u32 s48, s75, s90
	v_lshlrev_b64 v[0:1], 8, v[0:1]
	s_addc_u32 s49, s76, s91
	s_mov_b32 m0, s53
	v_lshl_add_u64 v[0:1], v[86:87], 0, v[0:1]
	s_waitcnt lgkmcnt(0)
	v_lshl_add_u64 v[18:19], s[48:49], 0, v[84:85]
	global_load_dwordx4 v[12:15], v[0:1], off
	global_load_dwordx4 v[8:11], v[0:1], off offset:64
	global_load_dwordx4 v[4:7], v[0:1], off offset:128
	s_nop 0
	global_load_dwordx4 v[0:3], v[0:1], off offset:192
	v_lshlrev_b64 v[16:17], 12, v[16:17]
	global_load_lds_dwordx4 v[18:19], off
	v_lshl_add_u64 v[18:19], s[48:49], 0, v[88:89]
	s_min_i32 s48, s77, 1
	s_ashr_i32 s49, s48, 31
	s_lshl_b64 s[80:81], s[48:49], 14
	s_add_u32 s48, s75, s80
	s_mov_b32 m0, s92
	s_addc_u32 s49, s76, s81
	global_load_lds_dwordx4 v[18:19], off
	v_lshl_add_u64 v[18:19], s[48:49], 0, v[84:85]
	s_mov_b32 m0, s93
	v_lshl_add_u64 v[16:17], s[84:85], 0, v[16:17]
	global_load_lds_dwordx4 v[18:19], off
	v_lshl_add_u64 v[18:19], s[48:49], 0, v[88:89]
	s_min_i32 s48, s77, 2
	s_ashr_i32 s49, s48, 31
	s_lshl_b64 s[70:71], s[48:49], 14
	s_add_u32 s48, s75, s70
	s_mov_b32 m0, s96
	s_addc_u32 s49, s76, s71
	global_load_lds_dwordx4 v[18:19], off
	v_lshl_add_u64 v[18:19], s[48:49], 0, v[84:85]
	s_mov_b32 m0, s97
	v_lshl_add_u64 v[16:17], s[38:39], 1, v[16:17]
	global_load_lds_dwordx4 v[18:19], off
	v_lshl_add_u64 v[18:19], s[48:49], 0, v[88:89]
	s_min_i32 s48, s77, 3
	s_ashr_i32 s49, s48, 31
	s_lshl_b64 s[68:69], s[48:49], 14
	s_add_u32 s48, s75, s68
	s_mov_b32 m0, s4
	s_addc_u32 s49, s76, s69
	global_load_lds_dwordx4 v[18:19], off
	v_lshl_add_u64 v[18:19], s[48:49], 0, v[84:85]
	s_mov_b32 m0, s5
	v_lshl_add_u64 v[90:91], v[80:81], 1, v[16:17]
	global_load_lds_dwordx4 v[18:19], off
	v_lshl_add_u64 v[18:19], s[48:49], 0, v[88:89]
	s_min_i32 s48, s77, 4
	s_ashr_i32 s49, s48, 31
	s_lshl_b64 s[64:65], s[48:49], 14
	s_add_u32 s48, s75, s64
	s_mov_b32 m0, s88
	s_addc_u32 s49, s76, s65
	global_load_lds_dwordx4 v[18:19], off
	v_lshl_add_u64 v[18:19], s[48:49], 0, v[84:85]
	s_mov_b32 m0, s54
	v_lshl_add_u32 v135, v107, 2, s74
	global_load_lds_dwordx4 v[18:19], off
	v_lshl_add_u64 v[18:19], s[48:49], 0, v[88:89]
	s_min_i32 s48, s77, 5
	s_ashr_i32 s49, s48, 31
	s_lshl_b64 s[60:61], s[48:49], 14
	s_add_u32 s48, s75, s60
	s_mov_b32 m0, s55
	s_addc_u32 s49, s76, s61
	global_load_lds_dwordx4 v[18:19], off
	v_lshl_add_u64 v[18:19], s[48:49], 0, v[84:85]
	s_mov_b32 m0, s56
	s_nop 0
	global_load_lds_dwordx4 v[18:19], off
	v_lshl_add_u64 v[18:19], s[48:49], 0, v[88:89]
	s_min_i32 s48, s77, 6
	s_ashr_i32 s49, s48, 31
	s_lshl_b64 s[58:59], s[48:49], 14
	s_add_u32 s48, s75, s58
	s_mov_b32 m0, s57
	s_addc_u32 s49, s76, s59
	global_load_lds_dwordx4 v[18:19], off
	v_lshl_add_u64 v[18:19], s[48:49], 0, v[84:85]
	s_mov_b32 m0, s62
	s_min_i32 s38, s77, 7
	global_load_lds_dwordx4 v[18:19], off
	v_lshl_add_u64 v[18:19], s[48:49], 0, v[88:89]
	s_mov_b32 m0, s63
	s_ashr_i32 s39, s38, 31
	global_load_lds_dwordx4 v[18:19], off
	s_lshl_b64 s[48:49], s[38:39], 14
	s_add_u32 s38, s75, s48
	s_addc_u32 s39, s76, s49
	v_lshl_add_u64 v[94:95], s[38:39], 0, v[84:85]
	v_lshl_add_u64 v[92:93], s[38:39], 0, v[88:89]
	s_mov_b64 s[38:39], -1
	s_and_b64 vcc, exec, s[2:3]
	s_cbranch_vccnz .LBB0_996
	s_mov_b32 s2, 0
	s_min_i32 s2, s77, 8
	s_ashr_i32 s3, s2, 31
	s_lshl_b64 s[38:39], s[2:3], 14
	s_waitcnt vmcnt(12)
	s_barrier
	s_mov_b32 m0, s66
	s_add_u32 s2, s75, s38
	global_load_lds_dwordx4 v[94:95], off
	s_mov_b32 m0, s67
	s_movk_i32 s78, 0x4000
	s_addc_u32 s3, s76, s39
	global_load_lds_dwordx4 v[92:93], off
	s_waitcnt vmcnt(12)
	s_barrier
	v_lshl_add_u64 v[16:17], s[2:3], 0, v[84:85]
	s_mov_b32 m0, s53
	s_nop 0
	global_load_lds_dwordx4 v[16:17], off
	v_lshl_add_u64 v[16:17], s[2:3], 0, v[88:89]
	s_add_i32 s2, s78, 0
	s_mov_b32 m0, s92
	v_add_u32_e32 v24, s2, v97
	global_load_lds_dwordx4 v[16:17], off
	v_add_u32_e32 v16, v24, v99
	ds_read_b128 v[16:19], v16
	v_add_u32_e32 v20, v24, v100
	ds_read_b128 v[20:23], v20
	s_waitcnt lgkmcnt(0)
	v_mfma_f32_16x16x32_bf16 v[16:19], v[16:19], v[12:15], 0
	s_mov_b32 s78, 0x8000
	s_mov_b32 m0, s93
	v_mfma_f32_16x16x32_bf16 v[16:19], v[20:23], v[8:11], v[16:19]
	v_add_u32_e32 v20, v24, v101
	ds_read_b128 v[20:23], v20
	s_waitcnt lgkmcnt(0)
	v_mfma_f32_16x16x32_bf16 v[16:19], v[20:23], v[4:7], v[16:19]
	v_add_u32_e32 v20, v24, v102
	ds_read_b128 v[20:23], v20
	v_add_u32_e32 v24, s2, v98
	s_waitcnt lgkmcnt(0)
	v_mfma_f32_16x16x32_bf16 v[48:51], v[20:23], v[0:3], v[16:19]
	s_nop 2
	v_add_u32_e32 v16, v24, v103
	ds_read_b128 v[16:19], v16
	v_add_u32_e32 v20, v24, v104
	ds_read_b128 v[20:23], v20
	s_waitcnt lgkmcnt(1)
	v_mfma_f32_16x16x32_bf16 v[16:19], v[16:19], v[12:15], 0
	s_add_u32 s2, s72, s90
	s_addc_u32 s3, s73, s91
	s_waitcnt lgkmcnt(0)
	v_mfma_f32_16x16x32_bf16 v[16:19], v[20:23], v[8:11], v[16:19]
	v_add_u32_e32 v20, v24, v105
	ds_read_b128 v[20:23], v20
	s_waitcnt lgkmcnt(0)
	v_mfma_f32_16x16x32_bf16 v[16:19], v[20:23], v[4:7], v[16:19]
	v_add_u32_e32 v20, v24, v106
	ds_read_b128 v[20:23], v20
	s_waitcnt vmcnt(12)
	s_barrier
	s_waitcnt lgkmcnt(0)
	v_mfma_f32_16x16x32_bf16 v[16:19], v[20:23], v[0:3], v[16:19]
	v_lshl_add_u64 v[20:21], s[2:3], 0, v[84:85]
	global_load_lds_dwordx4 v[20:21], off
	v_lshl_add_u64 v[20:21], s[2:3], 0, v[88:89]
	s_add_i32 s2, s78, 0
	s_mov_b32 m0, s96
	v_add_u32_e32 v28, s2, v97
	global_load_lds_dwordx4 v[20:21], off
	v_add_u32_e32 v20, v28, v99
	ds_read_b128 v[20:23], v20
	v_add_u32_e32 v24, v28, v100
	ds_read_b128 v[24:27], v24
	s_waitcnt lgkmcnt(0)
	v_mfma_f32_16x16x32_bf16 v[20:23], v[20:23], v[12:15], 0
	s_mov_b32 s78, 0xc000
	s_mov_b32 m0, s97
	v_mfma_f32_16x16x32_bf16 v[20:23], v[24:27], v[8:11], v[20:23]
	v_add_u32_e32 v24, v28, v101
	ds_read_b128 v[24:27], v24
	s_waitcnt lgkmcnt(0)
	v_mfma_f32_16x16x32_bf16 v[20:23], v[24:27], v[4:7], v[20:23]
	v_add_u32_e32 v24, v28, v102
	ds_read_b128 v[24:27], v24
	v_add_u32_e32 v28, s2, v98
	s_waitcnt lgkmcnt(0)
	v_mfma_f32_16x16x32_bf16 v[52:55], v[24:27], v[0:3], v[20:23]
	s_nop 2
	v_add_u32_e32 v20, v28, v103
	ds_read_b128 v[20:23], v20
	v_add_u32_e32 v24, v28, v104
	ds_read_b128 v[24:27], v24
	s_waitcnt lgkmcnt(0)
	v_mfma_f32_16x16x32_bf16 v[20:23], v[20:23], v[12:15], 0
	s_add_u32 s2, s72, s80
	s_addc_u32 s3, s73, s81
	v_mfma_f32_16x16x32_bf16 v[20:23], v[24:27], v[8:11], v[20:23]
	v_add_u32_e32 v24, v28, v105
	ds_read_b128 v[24:27], v24
	s_waitcnt lgkmcnt(0)
	v_mfma_f32_16x16x32_bf16 v[20:23], v[24:27], v[4:7], v[20:23]
	v_add_u32_e32 v24, v28, v106
	ds_read_b128 v[24:27], v24
	s_waitcnt vmcnt(12)
	s_barrier
	s_waitcnt lgkmcnt(0)
	v_mfma_f32_16x16x32_bf16 v[20:23], v[24:27], v[0:3], v[20:23]
	v_lshl_add_u64 v[24:25], s[2:3], 0, v[84:85]
	global_load_lds_dwordx4 v[24:25], off
	v_lshl_add_u64 v[24:25], s[2:3], 0, v[88:89]
	s_add_i32 s2, s78, 0
	s_mov_b32 m0, s4
	v_add_u32_e32 v32, s2, v97
	global_load_lds_dwordx4 v[24:25], off
	v_add_u32_e32 v24, v32, v99
	ds_read_b128 v[24:27], v24
	v_add_u32_e32 v28, v32, v100
	ds_read_b128 v[28:31], v28
	s_waitcnt lgkmcnt(0)
	v_mfma_f32_16x16x32_bf16 v[24:27], v[24:27], v[12:15], 0
	s_mov_b32 s78, 0x10000
	s_mov_b32 m0, s5
	v_mfma_f32_16x16x32_bf16 v[24:27], v[28:31], v[8:11], v[24:27]
	v_add_u32_e32 v28, v32, v101
	ds_read_b128 v[28:31], v28
	s_waitcnt lgkmcnt(0)
	v_mfma_f32_16x16x32_bf16 v[24:27], v[28:31], v[4:7], v[24:27]
	v_add_u32_e32 v28, v32, v102
	ds_read_b128 v[28:31], v28
	v_add_u32_e32 v32, s2, v98
	s_waitcnt lgkmcnt(0)
	v_mfma_f32_16x16x32_bf16 v[56:59], v[28:31], v[0:3], v[24:27]
	s_nop 2
	v_add_u32_e32 v24, v32, v103
	ds_read_b128 v[24:27], v24
	v_add_u32_e32 v28, v32, v104
	ds_read_b128 v[28:31], v28
	s_waitcnt lgkmcnt(0)
	v_mfma_f32_16x16x32_bf16 v[24:27], v[24:27], v[12:15], 0
	s_add_u32 s2, s72, s70
	s_addc_u32 s3, s73, s71
	v_mfma_f32_16x16x32_bf16 v[24:27], v[28:31], v[8:11], v[24:27]
	v_add_u32_e32 v28, v32, v105
	ds_read_b128 v[28:31], v28
	s_waitcnt lgkmcnt(0)
	v_mfma_f32_16x16x32_bf16 v[24:27], v[28:31], v[4:7], v[24:27]
	v_add_u32_e32 v28, v32, v106
	ds_read_b128 v[28:31], v28
	s_waitcnt vmcnt(12)
	s_barrier
	s_waitcnt lgkmcnt(0)
	v_mfma_f32_16x16x32_bf16 v[24:27], v[28:31], v[0:3], v[24:27]
	v_lshl_add_u64 v[28:29], s[2:3], 0, v[84:85]
	global_load_lds_dwordx4 v[28:29], off
	v_lshl_add_u64 v[28:29], s[2:3], 0, v[88:89]
	s_add_i32 s2, s78, 0
	s_mov_b32 m0, s88
	v_add_u32_e32 v36, s2, v97
	global_load_lds_dwordx4 v[28:29], off
	v_add_u32_e32 v28, v36, v99
	ds_read_b128 v[28:31], v28
	v_add_u32_e32 v32, v36, v100
	ds_read_b128 v[32:35], v32
	s_waitcnt lgkmcnt(0)
	v_mfma_f32_16x16x32_bf16 v[28:31], v[28:31], v[12:15], 0
	s_mov_b32 s78, 0x14000
	s_mov_b32 m0, s54
	v_mfma_f32_16x16x32_bf16 v[28:31], v[32:35], v[8:11], v[28:31]
	v_add_u32_e32 v32, v36, v101
	ds_read_b128 v[32:35], v32
	s_waitcnt lgkmcnt(0)
	v_mfma_f32_16x16x32_bf16 v[28:31], v[32:35], v[4:7], v[28:31]
	v_add_u32_e32 v32, v36, v102
	ds_read_b128 v[32:35], v32
	v_add_u32_e32 v36, s2, v98
	s_waitcnt lgkmcnt(0)
	v_mfma_f32_16x16x32_bf16 v[60:63], v[32:35], v[0:3], v[28:31]
	s_nop 2
	v_add_u32_e32 v28, v36, v103
	ds_read_b128 v[28:31], v28
	v_add_u32_e32 v32, v36, v104
	ds_read_b128 v[32:35], v32
	s_waitcnt lgkmcnt(0)
	v_mfma_f32_16x16x32_bf16 v[28:31], v[28:31], v[12:15], 0
	s_add_u32 s2, s72, s68
	s_addc_u32 s3, s73, s69
	v_mfma_f32_16x16x32_bf16 v[28:31], v[32:35], v[8:11], v[28:31]
	v_add_u32_e32 v32, v36, v105
	ds_read_b128 v[32:35], v32
	s_waitcnt lgkmcnt(0)
	v_mfma_f32_16x16x32_bf16 v[28:31], v[32:35], v[4:7], v[28:31]
	v_add_u32_e32 v32, v36, v106
	ds_read_b128 v[32:35], v32
	s_waitcnt vmcnt(12)
	s_barrier
	s_waitcnt lgkmcnt(0)
	v_mfma_f32_16x16x32_bf16 v[28:31], v[32:35], v[0:3], v[28:31]
	v_lshl_add_u64 v[32:33], s[2:3], 0, v[84:85]
	global_load_lds_dwordx4 v[32:33], off
	v_lshl_add_u64 v[32:33], s[2:3], 0, v[88:89]
	s_add_i32 s2, s78, 0
	s_mov_b32 m0, s55
	v_add_u32_e32 v40, s2, v97
	global_load_lds_dwordx4 v[32:33], off
	v_add_u32_e32 v32, v40, v99
	ds_read_b128 v[32:35], v32
	v_add_u32_e32 v36, v40, v100
	ds_read_b128 v[36:39], v36
	s_waitcnt lgkmcnt(0)
	v_mfma_f32_16x16x32_bf16 v[32:35], v[32:35], v[12:15], 0
	s_mov_b32 s78, 0x18000
	s_mov_b32 m0, s56
	v_mfma_f32_16x16x32_bf16 v[32:35], v[36:39], v[8:11], v[32:35]
	v_add_u32_e32 v36, v40, v101
	ds_read_b128 v[36:39], v36
	s_waitcnt lgkmcnt(0)
	v_mfma_f32_16x16x32_bf16 v[32:35], v[36:39], v[4:7], v[32:35]
	v_add_u32_e32 v36, v40, v102
	ds_read_b128 v[36:39], v36
	v_add_u32_e32 v40, s2, v98
	s_waitcnt lgkmcnt(0)
	v_mfma_f32_16x16x32_bf16 v[64:67], v[36:39], v[0:3], v[32:35]
	s_nop 2
	v_add_u32_e32 v32, v40, v103
	ds_read_b128 v[32:35], v32
	v_add_u32_e32 v36, v40, v104
	ds_read_b128 v[36:39], v36
	s_waitcnt lgkmcnt(0)
	v_mfma_f32_16x16x32_bf16 v[32:35], v[32:35], v[12:15], 0
	s_add_u32 s2, s72, s64
	s_addc_u32 s3, s73, s65
	v_mfma_f32_16x16x32_bf16 v[32:35], v[36:39], v[8:11], v[32:35]
	v_add_u32_e32 v36, v40, v105
	ds_read_b128 v[36:39], v36
	s_waitcnt lgkmcnt(0)
	v_mfma_f32_16x16x32_bf16 v[32:35], v[36:39], v[4:7], v[32:35]
	v_add_u32_e32 v36, v40, v106
	ds_read_b128 v[36:39], v36
	s_waitcnt vmcnt(12)
	s_barrier
	s_waitcnt lgkmcnt(0)
	v_mfma_f32_16x16x32_bf16 v[32:35], v[36:39], v[0:3], v[32:35]
	v_lshl_add_u64 v[36:37], s[2:3], 0, v[84:85]
	global_load_lds_dwordx4 v[36:37], off
	v_lshl_add_u64 v[36:37], s[2:3], 0, v[88:89]
	s_add_i32 s2, s78, 0
	s_mov_b32 m0, s57
	v_add_u32_e32 v44, s2, v97
	global_load_lds_dwordx4 v[36:37], off
	v_add_u32_e32 v36, v44, v99
	ds_read_b128 v[36:39], v36
	v_add_u32_e32 v40, v44, v100
	ds_read_b128 v[40:43], v40
	s_waitcnt lgkmcnt(0)
	v_mfma_f32_16x16x32_bf16 v[36:39], v[36:39], v[12:15], 0
	s_mov_b32 s78, 0x1c000
	s_mov_b32 m0, s62
	v_mfma_f32_16x16x32_bf16 v[36:39], v[40:43], v[8:11], v[36:39]
	v_add_u32_e32 v40, v44, v101
	ds_read_b128 v[40:43], v40
	s_waitcnt lgkmcnt(0)
	v_mfma_f32_16x16x32_bf16 v[36:39], v[40:43], v[4:7], v[36:39]
	v_add_u32_e32 v40, v44, v102
	ds_read_b128 v[40:43], v40
	v_add_u32_e32 v44, s2, v98
	s_waitcnt lgkmcnt(0)
	v_mfma_f32_16x16x32_bf16 v[68:71], v[40:43], v[0:3], v[36:39]
	s_nop 2
	v_add_u32_e32 v36, v44, v103
	ds_read_b128 v[36:39], v36
	v_add_u32_e32 v40, v44, v104
	ds_read_b128 v[40:43], v40
	s_waitcnt lgkmcnt(0)
	v_mfma_f32_16x16x32_bf16 v[36:39], v[36:39], v[12:15], 0
	s_add_u32 s2, s72, s60
	s_addc_u32 s3, s73, s61
	v_mfma_f32_16x16x32_bf16 v[36:39], v[40:43], v[8:11], v[36:39]
	v_add_u32_e32 v40, v44, v105
	ds_read_b128 v[40:43], v40
	s_waitcnt lgkmcnt(0)
	v_mfma_f32_16x16x32_bf16 v[36:39], v[40:43], v[4:7], v[36:39]
	v_add_u32_e32 v40, v44, v106
	ds_read_b128 v[40:43], v40
	s_waitcnt vmcnt(12)
	s_barrier
	s_waitcnt lgkmcnt(0)
	v_mfma_f32_16x16x32_bf16 v[36:39], v[40:43], v[0:3], v[36:39]
	v_lshl_add_u64 v[40:41], s[2:3], 0, v[84:85]
	global_load_lds_dwordx4 v[40:41], off
	v_lshl_add_u64 v[40:41], s[2:3], 0, v[88:89]
	s_add_i32 s2, s78, 0
	s_mov_b32 m0, s63
	v_add_u32_e32 v72, s2, v97
	global_load_lds_dwordx4 v[40:41], off
	v_add_u32_e32 v40, v72, v99
	ds_read_b128 v[40:43], v40
	v_add_u32_e32 v44, v72, v100
	ds_read_b128 v[44:47], v44
	s_waitcnt lgkmcnt(0)
	v_mfma_f32_16x16x32_bf16 v[40:43], v[40:43], v[12:15], 0
	v_add_u32_e32 v76, s2, v98
	s_add_u32 s2, s72, s58
	s_mov_b32 s78, 0
	v_mfma_f32_16x16x32_bf16 v[40:43], v[44:47], v[8:11], v[40:43]
	v_add_u32_e32 v44, v72, v101
	ds_read_b128 v[44:47], v44
	s_addc_u32 s3, s73, s59
	s_waitcnt lgkmcnt(0)
	v_mfma_f32_16x16x32_bf16 v[40:43], v[44:47], v[4:7], v[40:43]
	v_add_u32_e32 v44, v72, v102
	ds_read_b128 v[44:47], v44
	s_mov_b32 m0, s66
	s_waitcnt lgkmcnt(0)
	v_mfma_f32_16x16x32_bf16 v[72:75], v[44:47], v[0:3], v[40:43]
	s_nop 2
	v_add_u32_e32 v40, v76, v103
	ds_read_b128 v[40:43], v40
	v_add_u32_e32 v44, v76, v104
	ds_read_b128 v[44:47], v44
	s_waitcnt lgkmcnt(0)
	v_mfma_f32_16x16x32_bf16 v[40:43], v[40:43], v[12:15], 0
	v_mfma_f32_16x16x32_bf16 v[40:43], v[44:47], v[8:11], v[40:43]
	v_add_u32_e32 v44, v76, v105
	ds_read_b128 v[44:47], v44
	s_waitcnt lgkmcnt(0)
	v_mfma_f32_16x16x32_bf16 v[40:43], v[44:47], v[4:7], v[40:43]
	v_add_u32_e32 v44, v76, v106
	ds_read_b128 v[44:47], v44
	s_waitcnt vmcnt(12)
	s_barrier
	s_waitcnt lgkmcnt(0)
	v_mfma_f32_16x16x32_bf16 v[40:43], v[44:47], v[0:3], v[40:43]
	v_lshl_add_u64 v[44:45], s[2:3], 0, v[84:85]
	global_load_lds_dwordx4 v[44:45], off
	v_lshl_add_u64 v[44:45], s[2:3], 0, v[88:89]
	s_mov_b32 m0, s67
	s_add_i32 s2, s78, 0
	global_load_lds_dwordx4 v[44:45], off
	v_add_u32_e32 v136, s2, v97
	v_add_u32_e32 v44, v136, v99
	ds_read_b128 v[44:47], v44
	v_add_u32_e32 v76, v136, v100
	ds_read_b128 v[76:79], v76
	s_waitcnt lgkmcnt(0)
	v_mfma_f32_16x16x32_bf16 v[44:47], v[44:47], v[12:15], 0
	v_add_u32_e32 v140, s2, v98
	v_mfma_f32_16x16x32_bf16 v[44:47], v[76:79], v[8:11], v[44:47]
	v_add_u32_e32 v76, v136, v101
	ds_read_b128 v[76:79], v76
	s_waitcnt lgkmcnt(0)
	v_mfma_f32_16x16x32_bf16 v[44:47], v[76:79], v[4:7], v[44:47]
	v_add_u32_e32 v76, v136, v102
	ds_read_b128 v[76:79], v76
	v_add_u32_e32 v136, v140, v104
	s_waitcnt lgkmcnt(0)
	v_mfma_f32_16x16x32_bf16 v[76:79], v[76:79], v[0:3], v[44:47]
	s_nop 2
	v_add_u32_e32 v44, v140, v103
	ds_read_b128 v[44:47], v44
	ds_read_b128 v[136:139], v136
	s_waitcnt lgkmcnt(0)
	v_mfma_f32_16x16x32_bf16 v[44:47], v[44:47], v[12:15], 0
	v_mfma_f32_16x16x32_bf16 v[44:47], v[136:139], v[8:11], v[44:47]
	v_add_u32_e32 v136, v140, v105
	ds_read_b128 v[136:139], v136
	s_waitcnt lgkmcnt(0)
	v_mfma_f32_16x16x32_bf16 v[44:47], v[136:139], v[4:7], v[44:47]
	v_add_u32_e32 v136, v140, v106
	ds_read_b128 v[136:139], v136
	s_waitcnt lgkmcnt(0)
	v_mfma_f32_16x16x32_bf16 v[44:47], v[136:139], v[0:3], v[44:47]
	v_mov_b32_e32 v138, 0xf149f2ca
	v_mov_b32_e32 v139, 0xf149f2ca
	s_and_saveexec_b64 s[2:3], s[10:11]
	s_cbranch_execz .LBB0_869
	ds_read_b32 v136, v135 offset:868
	s_waitcnt lgkmcnt(0)
	v_add_f32_e32 v139, v48, v136

.LBB0_996:
	s_and_b64 vcc, exec, s[38:39]
	s_cbranch_vccz .LBB0_853
	s_mov_b32 s2, 0
	s_waitcnt vmcnt(12)
	s_barrier
	s_mov_b32 m0, s66
	s_add_i32 s2, s2, 0
	global_load_lds_dwordx4 v[94:95], off
	s_mov_b32 m0, s67
	v_add_u32_e32 v24, s2, v97
	global_load_lds_dwordx4 v[92:93], off
	v_add_u32_e32 v16, v24, v99
	ds_read_b128 v[16:19], v16
	v_add_u32_e32 v20, v24, v100
	ds_read_b128 v[20:23], v20
	s_waitcnt lgkmcnt(0)
	v_mfma_f32_16x16x32_bf16 v[16:19], v[16:19], v[12:15], 0
	s_movk_i32 s78, 0x4000
	s_mov_b32 m0, s53
	v_mfma_f32_16x16x32_bf16 v[16:19], v[20:23], v[8:11], v[16:19]
	v_add_u32_e32 v20, v24, v101
	ds_read_b128 v[20:23], v20
	s_waitcnt lgkmcnt(0)
	v_mfma_f32_16x16x32_bf16 v[16:19], v[20:23], v[4:7], v[16:19]
	v_add_u32_e32 v20, v24, v102
	ds_read_b128 v[20:23], v20
	v_add_u32_e32 v24, s2, v98
	s_waitcnt lgkmcnt(0)
	v_mfma_f32_16x16x32_bf16 v[44:47], v[20:23], v[0:3], v[16:19]
	s_nop 2
	v_add_u32_e32 v16, v24, v103
	ds_read_b128 v[16:19], v16
	v_add_u32_e32 v20, v24, v104
	ds_read_b128 v[20:23], v20
	s_waitcnt lgkmcnt(1)
	v_mfma_f32_16x16x32_bf16 v[16:19], v[16:19], v[12:15], 0
	s_min_i32 s2, s77, 8
	s_ashr_i32 s3, s2, 31
	s_lshl_b64 s[38:39], s[2:3], 14
	s_waitcnt lgkmcnt(0)
	v_mfma_f32_16x16x32_bf16 v[16:19], v[20:23], v[8:11], v[16:19]
	v_add_u32_e32 v20, v24, v105
	ds_read_b128 v[20:23], v20
	s_add_u32 s2, s75, s38
	s_waitcnt lgkmcnt(0)
	v_mfma_f32_16x16x32_bf16 v[16:19], v[20:23], v[4:7], v[16:19]
	v_add_u32_e32 v20, v24, v106
	ds_read_b128 v[20:23], v20
	s_addc_u32 s3, s76, s39
	s_waitcnt lgkmcnt(0)
	v_mfma_f32_16x16x32_bf16 v[16:19], v[20:23], v[0:3], v[16:19]
	s_waitcnt vmcnt(12)
	s_barrier
	v_lshl_add_u64 v[20:21], s[2:3], 0, v[84:85]
	global_load_lds_dwordx4 v[20:21], off
	v_lshl_add_u64 v[20:21], s[2:3], 0, v[88:89]
	s_add_i32 s2, s78, 0
	s_mov_b32 m0, s92
	v_add_u32_e32 v28, s2, v97
	global_load_lds_dwordx4 v[20:21], off
	v_add_u32_e32 v20, v28, v99
	ds_read_b128 v[20:23], v20
	v_add_u32_e32 v24, v28, v100
	ds_read_b128 v[24:27], v24
	s_waitcnt lgkmcnt(0)
	v_mfma_f32_16x16x32_bf16 v[20:23], v[20:23], v[12:15], 0
	s_mov_b32 s75, 0x8000
	s_mov_b32 m0, s93
	v_mfma_f32_16x16x32_bf16 v[20:23], v[24:27], v[8:11], v[20:23]
	v_add_u32_e32 v24, v28, v101
	ds_read_b128 v[24:27], v24
	s_waitcnt lgkmcnt(0)
	v_mfma_f32_16x16x32_bf16 v[20:23], v[24:27], v[4:7], v[20:23]
	v_add_u32_e32 v24, v28, v102
	ds_read_b128 v[24:27], v24
	v_add_u32_e32 v28, s2, v98
	s_waitcnt lgkmcnt(0)
	v_mfma_f32_16x16x32_bf16 v[48:51], v[24:27], v[0:3], v[20:23]
	s_nop 2
	v_add_u32_e32 v20, v28, v103
	ds_read_b128 v[20:23], v20
	v_add_u32_e32 v24, v28, v104
	ds_read_b128 v[24:27], v24
	s_waitcnt lgkmcnt(0)
	v_mfma_f32_16x16x32_bf16 v[20:23], v[20:23], v[12:15], 0
	s_add_u32 s2, s72, s90
	s_addc_u32 s3, s73, s91
	v_mfma_f32_16x16x32_bf16 v[20:23], v[24:27], v[8:11], v[20:23]
	v_add_u32_e32 v24, v28, v105
	ds_read_b128 v[24:27], v24
	s_waitcnt lgkmcnt(0)
	v_mfma_f32_16x16x32_bf16 v[20:23], v[24:27], v[4:7], v[20:23]
	v_add_u32_e32 v24, v28, v106
	ds_read_b128 v[24:27], v24
	s_waitcnt vmcnt(12)
	s_barrier
	s_waitcnt lgkmcnt(0)
	v_mfma_f32_16x16x32_bf16 v[20:23], v[24:27], v[0:3], v[20:23]
	v_lshl_add_u64 v[24:25], s[2:3], 0, v[84:85]
	global_load_lds_dwordx4 v[24:25], off
	v_lshl_add_u64 v[24:25], s[2:3], 0, v[88:89]
	s_add_i32 s2, s75, 0
	s_mov_b32 m0, s96
	v_add_u32_e32 v32, s2, v97
	global_load_lds_dwordx4 v[24:25], off
	v_add_u32_e32 v24, v32, v99
	ds_read_b128 v[24:27], v24
	v_add_u32_e32 v28, v32, v100
	ds_read_b128 v[28:31], v28
	s_waitcnt lgkmcnt(0)
	v_mfma_f32_16x16x32_bf16 v[24:27], v[24:27], v[12:15], 0
	s_mov_b32 s75, 0xc000
	s_mov_b32 m0, s97
	v_mfma_f32_16x16x32_bf16 v[24:27], v[28:31], v[8:11], v[24:27]
	v_add_u32_e32 v28, v32, v101
	ds_read_b128 v[28:31], v28
	s_waitcnt lgkmcnt(0)
	v_mfma_f32_16x16x32_bf16 v[24:27], v[28:31], v[4:7], v[24:27]
	v_add_u32_e32 v28, v32, v102
	ds_read_b128 v[28:31], v28
	v_add_u32_e32 v32, s2, v98
	s_waitcnt lgkmcnt(0)
	v_mfma_f32_16x16x32_bf16 v[52:55], v[28:31], v[0:3], v[24:27]
	s_nop 2
	v_add_u32_e32 v24, v32, v103
	ds_read_b128 v[24:27], v24
	v_add_u32_e32 v28, v32, v104
	ds_read_b128 v[28:31], v28
	s_waitcnt lgkmcnt(0)
	v_mfma_f32_16x16x32_bf16 v[24:27], v[24:27], v[12:15], 0
	s_add_u32 s2, s72, s80
	s_addc_u32 s3, s73, s81
	v_mfma_f32_16x16x32_bf16 v[24:27], v[28:31], v[8:11], v[24:27]
	v_add_u32_e32 v28, v32, v105
	ds_read_b128 v[28:31], v28
	s_waitcnt lgkmcnt(0)
	v_mfma_f32_16x16x32_bf16 v[24:27], v[28:31], v[4:7], v[24:27]
	v_add_u32_e32 v28, v32, v106
	ds_read_b128 v[28:31], v28
	s_waitcnt vmcnt(12)
	s_barrier
	s_waitcnt lgkmcnt(0)
	v_mfma_f32_16x16x32_bf16 v[24:27], v[28:31], v[0:3], v[24:27]
	v_lshl_add_u64 v[28:29], s[2:3], 0, v[84:85]
	global_load_lds_dwordx4 v[28:29], off
	v_lshl_add_u64 v[28:29], s[2:3], 0, v[88:89]
	s_add_i32 s2, s75, 0
	s_mov_b32 m0, s4
	v_add_u32_e32 v36, s2, v97
	global_load_lds_dwordx4 v[28:29], off
	v_add_u32_e32 v28, v36, v99
	ds_read_b128 v[28:31], v28
	v_add_u32_e32 v32, v36, v100
	ds_read_b128 v[32:35], v32
	s_waitcnt lgkmcnt(0)
	v_mfma_f32_16x16x32_bf16 v[28:31], v[28:31], v[12:15], 0
	s_mov_b32 s75, 0x10000
	s_mov_b32 m0, s5
	v_mfma_f32_16x16x32_bf16 v[28:31], v[32:35], v[8:11], v[28:31]
	v_add_u32_e32 v32, v36, v101
	ds_read_b128 v[32:35], v32
	s_waitcnt lgkmcnt(0)
	v_mfma_f32_16x16x32_bf16 v[28:31], v[32:35], v[4:7], v[28:31]
	v_add_u32_e32 v32, v36, v102
	ds_read_b128 v[32:35], v32
	v_add_u32_e32 v36, s2, v98
	s_waitcnt lgkmcnt(0)
	v_mfma_f32_16x16x32_bf16 v[56:59], v[32:35], v[0:3], v[28:31]
	s_nop 2
	v_add_u32_e32 v28, v36, v103
	ds_read_b128 v[28:31], v28
	v_add_u32_e32 v32, v36, v104
	ds_read_b128 v[32:35], v32
	s_waitcnt lgkmcnt(0)
	v_mfma_f32_16x16x32_bf16 v[28:31], v[28:31], v[12:15], 0
	s_add_u32 s2, s72, s70
	s_addc_u32 s3, s73, s71
	s_mov_b32 s70, 0x14000
	v_mfma_f32_16x16x32_bf16 v[28:31], v[32:35], v[8:11], v[28:31]
	v_add_u32_e32 v32, v36, v105
	ds_read_b128 v[32:35], v32
	s_waitcnt lgkmcnt(0)
	v_mfma_f32_16x16x32_bf16 v[28:31], v[32:35], v[4:7], v[28:31]
	v_add_u32_e32 v32, v36, v106
	ds_read_b128 v[32:35], v32
	s_waitcnt vmcnt(12)
	s_barrier
	s_waitcnt lgkmcnt(0)
	v_mfma_f32_16x16x32_bf16 v[28:31], v[32:35], v[0:3], v[28:31]
	v_lshl_add_u64 v[32:33], s[2:3], 0, v[84:85]
	global_load_lds_dwordx4 v[32:33], off
	v_lshl_add_u64 v[32:33], s[2:3], 0, v[88:89]
	s_add_i32 s2, s75, 0
	s_mov_b32 m0, s88
	v_add_u32_e32 v40, s2, v97
	global_load_lds_dwordx4 v[32:33], off
	v_add_u32_e32 v32, v40, v99
	ds_read_b128 v[32:35], v32
	v_add_u32_e32 v36, v40, v100
	ds_read_b128 v[36:39], v36
	s_waitcnt lgkmcnt(0)
	v_mfma_f32_16x16x32_bf16 v[32:35], v[32:35], v[12:15], 0
	s_mov_b32 m0, s54
	v_mfma_f32_16x16x32_bf16 v[32:35], v[36:39], v[8:11], v[32:35]
	v_add_u32_e32 v36, v40, v101
	ds_read_b128 v[36:39], v36
	s_waitcnt lgkmcnt(0)
	v_mfma_f32_16x16x32_bf16 v[32:35], v[36:39], v[4:7], v[32:35]
	v_add_u32_e32 v36, v40, v102
	ds_read_b128 v[36:39], v36
	v_add_u32_e32 v40, s2, v98
	s_waitcnt lgkmcnt(0)
	v_mfma_f32_16x16x32_bf16 v[60:63], v[36:39], v[0:3], v[32:35]
	s_nop 2
	v_add_u32_e32 v32, v40, v103
	ds_read_b128 v[32:35], v32
	v_add_u32_e32 v36, v40, v104
	ds_read_b128 v[36:39], v36
	s_waitcnt lgkmcnt(0)
	v_mfma_f32_16x16x32_bf16 v[32:35], v[32:35], v[12:15], 0
	s_add_u32 s2, s72, s68
	s_addc_u32 s3, s73, s69
	s_mov_b32 s68, 0x18000
	v_mfma_f32_16x16x32_bf16 v[32:35], v[36:39], v[8:11], v[32:35]
	v_add_u32_e32 v36, v40, v105
	ds_read_b128 v[36:39], v36
	s_waitcnt lgkmcnt(0)
	v_mfma_f32_16x16x32_bf16 v[32:35], v[36:39], v[4:7], v[32:35]
	v_add_u32_e32 v36, v40, v106
	ds_read_b128 v[36:39], v36
	s_waitcnt vmcnt(12)
	s_barrier
	s_waitcnt lgkmcnt(0)
	v_mfma_f32_16x16x32_bf16 v[32:35], v[36:39], v[0:3], v[32:35]
	v_lshl_add_u64 v[36:37], s[2:3], 0, v[84:85]
	global_load_lds_dwordx4 v[36:37], off
	v_lshl_add_u64 v[36:37], s[2:3], 0, v[88:89]
	s_add_i32 s2, s70, 0
	s_mov_b32 m0, s55
	v_add_u32_e32 v64, s2, v97
	global_load_lds_dwordx4 v[36:37], off
	v_add_u32_e32 v36, v64, v99
	ds_read_b128 v[36:39], v36
	v_add_u32_e32 v40, v64, v100
	ds_read_b128 v[40:43], v40
	s_waitcnt lgkmcnt(0)
	v_mfma_f32_16x16x32_bf16 v[36:39], v[36:39], v[12:15], 0
	v_add_u32_e32 v68, s2, v98
	s_add_u32 s2, s72, s64
	s_addc_u32 s3, s73, s65
	v_mfma_f32_16x16x32_bf16 v[36:39], v[40:43], v[8:11], v[36:39]
	v_add_u32_e32 v40, v64, v101
	ds_read_b128 v[40:43], v40
	s_mov_b32 m0, s56
	s_waitcnt lgkmcnt(0)
	v_mfma_f32_16x16x32_bf16 v[36:39], v[40:43], v[4:7], v[36:39]
	v_add_u32_e32 v40, v64, v102
	ds_read_b128 v[40:43], v40
	s_mov_b32 s64, 0x1c000
	s_waitcnt lgkmcnt(0)
	v_mfma_f32_16x16x32_bf16 v[64:67], v[40:43], v[0:3], v[36:39]
	s_nop 2
	v_add_u32_e32 v36, v68, v103
	ds_read_b128 v[36:39], v36
	v_add_u32_e32 v40, v68, v104
	ds_read_b128 v[40:43], v40
	s_waitcnt lgkmcnt(0)
	v_mfma_f32_16x16x32_bf16 v[36:39], v[36:39], v[12:15], 0
	v_mfma_f32_16x16x32_bf16 v[36:39], v[40:43], v[8:11], v[36:39]
	v_add_u32_e32 v40, v68, v105
	ds_read_b128 v[40:43], v40
	s_waitcnt lgkmcnt(0)
	v_mfma_f32_16x16x32_bf16 v[36:39], v[40:43], v[4:7], v[36:39]
	v_add_u32_e32 v40, v68, v106
	ds_read_b128 v[40:43], v40
	s_waitcnt vmcnt(12)
	s_barrier
	s_waitcnt lgkmcnt(0)
	v_mfma_f32_16x16x32_bf16 v[36:39], v[40:43], v[0:3], v[36:39]
	v_lshl_add_u64 v[40:41], s[2:3], 0, v[84:85]
	global_load_lds_dwordx4 v[40:41], off
	v_lshl_add_u64 v[40:41], s[2:3], 0, v[88:89]
	s_add_i32 s2, s68, 0
	s_mov_b32 m0, s57
	v_add_u32_e32 v72, s2, v97
	global_load_lds_dwordx4 v[40:41], off
	v_add_u32_e32 v40, v72, v99
	ds_read_b128 v[40:43], v40
	v_add_u32_e32 v68, v72, v100
	ds_read_b128 v[68:71], v68
	s_waitcnt lgkmcnt(0)
	v_mfma_f32_16x16x32_bf16 v[40:43], v[40:43], v[12:15], 0
	v_add_u32_e32 v76, s2, v98
	s_add_u32 s2, s72, s60
	s_addc_u32 s3, s73, s61
	v_mfma_f32_16x16x32_bf16 v[40:43], v[68:71], v[8:11], v[40:43]
	v_add_u32_e32 v68, v72, v101
	ds_read_b128 v[68:71], v68
	s_mov_b32 m0, s62
	s_waitcnt lgkmcnt(0)
	v_mfma_f32_16x16x32_bf16 v[40:43], v[68:71], v[4:7], v[40:43]
	v_add_u32_e32 v68, v72, v102
	ds_read_b128 v[68:71], v68
	v_add_u32_e32 v72, v76, v104
	s_waitcnt lgkmcnt(0)
	v_mfma_f32_16x16x32_bf16 v[68:71], v[68:71], v[0:3], v[40:43]
	s_nop 2
	v_add_u32_e32 v40, v76, v103
	ds_read_b128 v[40:43], v40
	ds_read_b128 v[72:75], v72
	s_waitcnt lgkmcnt(0)
	v_mfma_f32_16x16x32_bf16 v[40:43], v[40:43], v[12:15], 0
	v_mfma_f32_16x16x32_bf16 v[40:43], v[72:75], v[8:11], v[40:43]
	v_add_u32_e32 v72, v76, v105
	ds_read_b128 v[72:75], v72
	s_waitcnt lgkmcnt(0)
	v_mfma_f32_16x16x32_bf16 v[40:43], v[72:75], v[4:7], v[40:43]
	v_add_u32_e32 v72, v76, v106
	ds_read_b128 v[72:75], v72
	s_waitcnt vmcnt(12)
	s_barrier
	s_waitcnt lgkmcnt(0)
	v_mfma_f32_16x16x32_bf16 v[40:43], v[72:75], v[0:3], v[40:43]
	v_lshl_add_u64 v[72:73], s[2:3], 0, v[84:85]
	global_load_lds_dwordx4 v[72:73], off
	v_lshl_add_u64 v[72:73], s[2:3], 0, v[88:89]
	s_add_i32 s2, s64, 0
	s_mov_b32 m0, s63
	v_add_u32_e32 v92, s2, v97
	global_load_lds_dwordx4 v[72:73], off
	v_add_u32_e32 v72, v92, v99
	ds_read_b128 v[72:75], v72
	v_add_u32_e32 v76, v92, v100
	ds_read_b128 v[76:79], v76
	s_waitcnt lgkmcnt(0)
	v_mfma_f32_16x16x32_bf16 v[72:75], v[72:75], v[12:15], 0
	s_mov_b32 m0, s66
	v_mfma_f32_16x16x32_bf16 v[72:75], v[76:79], v[8:11], v[72:75]
	v_add_u32_e32 v76, v92, v101
	ds_read_b128 v[76:79], v76
	s_waitcnt lgkmcnt(0)
	v_mfma_f32_16x16x32_bf16 v[72:75], v[76:79], v[4:7], v[72:75]
	v_add_u32_e32 v76, v92, v102
	ds_read_b128 v[76:79], v76
	v_add_u32_e32 v92, s2, v98
	s_waitcnt lgkmcnt(0)
	v_mfma_f32_16x16x32_bf16 v[72:75], v[76:79], v[0:3], v[72:75]
	v_add_u32_e32 v76, v92, v103
	ds_read_b128 v[76:79], v76
	s_mov_b32 s2, 0
	s_waitcnt lgkmcnt(0)
	v_mfma_f32_16x16x32_bf16 v[12:15], v[76:79], v[12:15], 0
	v_add_u32_e32 v76, v92, v104
	ds_read_b128 v[76:79], v76
	s_waitcnt lgkmcnt(0)
	v_mfma_f32_16x16x32_bf16 v[8:11], v[76:79], v[8:11], v[12:15]
	s_nop 3
	v_add_u32_e32 v12, v92, v105
	ds_read_b128 v[12:15], v12
	s_waitcnt lgkmcnt(0)
	v_mfma_f32_16x16x32_bf16 v[4:7], v[12:15], v[4:7], v[8:11]
	s_nop 2
	v_add_u32_e32 v8, v92, v106
	ds_read_b128 v[8:11], v8
	s_add_u32 s2, s72, s58
	s_addc_u32 s3, s73, s59
	s_waitcnt lgkmcnt(0)
	v_mfma_f32_16x16x32_bf16 v[0:3], v[8:11], v[0:3], v[4:7]
	s_waitcnt vmcnt(12)
	s_barrier
	s_nop 1
	v_lshl_add_u64 v[4:5], s[2:3], 0, v[84:85]
	global_load_lds_dwordx4 v[4:5], off
	v_lshl_add_u64 v[4:5], s[2:3], 0, v[88:89]
	s_mov_b32 m0, s67
	v_mov_b32_e32 v9, 0xf149f2ca
	global_load_lds_dwordx4 v[4:5], off
	v_mov_b32_e32 v11, 0xf149f2ca
	s_and_saveexec_b64 s[2:3], s[10:11]
	s_cbranch_execz .LBB0_999
	ds_read_b32 v4, v135 offset:868
	s_waitcnt lgkmcnt(0)
	v_add_f32_e32 v11, v44, v4
